# scan loop: per-row sum of squares as one transposing DPP reduction + single LDS write (was 16 separate all-reduces with masked writes); phases 6/10 rmsnorm hand-written
# speedup vs baseline: 1.0054x; 1.0001x over previous
; #define LAS __attribute__((address_space(3)))
; #define BAR_LDS() do { asm volatile("s_waitcnt lgkmcnt(0)" ::: "memory"); __builtin_amdgcn_s_barrier(); asm volatile("" ::: "memory"); } while (0)
; #define SCAN_COPY(srcbase, bufidx) do { _Pragma("unroll") for (int k = 0; k < 8; ++k) { const int pc = wave + 8 * k; if (pc < IMG_PIECES) \
;         __builtin_amdgcn_global_load_lds((const unsigned*)((srcbase) + pc * 1024 + lane * 16), (LAS unsigned*)(lds + (bufidx) * IMG_BYTES + pc * 1024), 16, 0, 0); } } while (0)
; __device__ __forceinline__ void phase_scan(const Params& p, LAS unsigned char* lds, int bh, int wave_s) {
;     const int tid = opaque_tid(wave_s), lane = tid & 63, wave = __builtin_amdgcn_readfirstlane(tid >> 6), fr = lane & 15, fq = lane >> 4;
;     const int b = bh >> 4, h = bh & 15, e0 = wave * 16;
;     const bf16_t* PROJ = (const bf16_t*)(p.ws + WS_PROJ); bf16_t* GDN = (bf16_t*)(p.ws + WS_GDNOUT);
;     const float* GL = (const float*)(p.ws + WS_GL);
;     LAS float* SCR = (LAS float*)(lds + 2 * IMG_BYTES);
;     const float gnorm = p.in[14][e0 + fr];
;     f32x4 Sacc[8];
; #pragma unroll
;     for (int m = 0; m < 8; ++m) Sacc[m] = (f32x4){0.f, 0.f, 0.f, 0.f};
;     const int unit0 = bh * 32;
;     const unsigned char* chunk0 = (const unsigned char*)(p.ws + WS_CHUNK) + (size_t)unit0 * IMG_BYTES;
;     const float* U0 = p.out + O_YP + (size_t)unit0 * 8192 + ((wave * 256 + lane) << 2);
;     const bf16_t* Z0 = PROJ + ((size_t)b * SEQ + (tid >> 3)) * NQ + 7168 + h * 128 + (tid & 7) * 16;
;     LAS bf16_t* ZT = (LAS bf16_t*)(lds + 2 * IMG_BYTES + 4096);
;     LAS bf16_t* ztw = ZT + (tid >> 3) * 136 + (tid & 7) * 16;
;     ...
;     SCAN_COPY(chunk0, 0);
;     f32x4 ucur[4]; float glcur; u32x4 zr0, zr1;
;     SCAN_LOAD(0, ucur, zr0, zr1, glcur);
;     asm volatile("s_waitcnt vmcnt(0)" ::: "memory");
;     *(LAS u32x4*)ztw = zr0; *(LAS u32x4*)(ztw + 8) = zr1;
;     BAR_LDS();
;     ...
;             for (int rg = 0; rg < 4; ++rg) { const float sr = dpp_sum16(o[mm][rg] * o[mm][rg]);
;                 if (fr == 0) SCR[(16 * mm + 4 * fq + rg) * 8 + wave] = sr; }
.LBB0_916:
	s_ashr_i32 s56, s2, 4
	s_ashr_i32 s57, s56, 31
	v_ashrrev_i32_e32 v12, 3, v0
	s_lshl_b64 s[0:1], s[38:39], 15
	s_lshl_b64 s[36:37], s[56:57], 11
	v_ashrrev_i32_e32 v13, 31, v12
	s_add_i32 s58, 0, 0x1e800
	v_lshl_add_u64 v[4:5], s[36:37], 0, v[12:13]
	s_movk_i32 s5, 0x4800
	v_mov_b64_e32 v[6:7], s[22:23]
	s_add_u32 s48, s20, s0
	v_mad_u64_u32 v[6:7], s[36:37], v4, s5, v[6:7]
	s_addc_u32 s49, s21, s1
	s_lshl_b32 s0, s2, 8
	v_mad_i32_i24 v7, v5, s5, v7
	s_mov_b32 s37, 0
	s_and_b32 s36, s0, 0xf00
	v_lshlrev_b32_e32 v3, 5, v0
	v_lshl_add_u64 v[4:5], v[6:7], 0, s[36:37]
	v_and_b32_e32 v76, 0xe0, v3
	v_mov_b32_e32 v77, 0
	v_lshl_add_u64 v[4:5], v[4:5], 0, v[76:77]
	s_mov_b64 s[0:1], 0xa6ad800
	v_lshl_add_u64 v[78:79], v[4:5], 0, s[0:1]
	s_mov_b32 s0, 0xa6ad000
	v_add_co_u32_e32 v4, vcc, s0, v4
	v_lshlrev_b32_e32 v3, 2, v2
	s_nop 0
	v_addc_co_u32_e32 v5, vcc, 0, v5, vcc
	v_or_b32_e32 v14, s4, v3
	global_load_dwordx4 v[4:7], v[4:5], off offset:2048
	s_nop 0
	global_load_dwordx4 v[8:11], v[78:79], off offset:16
	v_ashrrev_i32_e32 v15, 31, v14
	s_lshl_b64 s[38:39], s[38:39], 2
	v_lshl_add_u64 v[80:81], v[14:15], 2, s[48:49]
	global_load_dwordx4 v[32:35], v[80:81], off
	global_load_dwordx4 v[36:39], v[80:81], off offset:1024
	global_load_dwordx4 v[40:43], v[80:81], off offset:2048
	global_load_dwordx4 v[44:47], v[80:81], off offset:3072
	s_add_u32 s38, s22, s38
	v_mov_b32_e32 v13, 0x64a8000
	s_addc_u32 s39, s23, s39
	global_load_dword v84, v13, s[38:39]
	s_movk_i32 s5, 0x110
	s_add_u32 s25, s38, 0x64a8000
	v_mul_lo_u32 v12, v12, s5
	s_addc_u32 s62, s39, 0
	s_lshl_b32 s36, s41, 2
	s_and_b32 s39, s40, 0x3fffffc0
	s_lshl_b32 s41, s50, 1
	v_lshrrev_b32_e32 v85, 4, v2
	v_lshlrev_b32_e32 v17, 5, v2
	v_and_b32_e32 v18, 48, v2
	v_lshlrev_b32_e32 v2, 1, v1
	v_add3_u32 v90, s58, v12, v76
	s_lshl_b32 s59, s39, 2
	s_add_i32 s58, s58, s41
	s_ashr_i32 s51, s50, 31
	s_lshl_b32 s38, s42, 10
	s_lshl_b32 s40, s43, 10
	s_lshl_b32 s42, s44, 10
	s_lshl_b32 s44, s45, 10
	s_lshl_b32 s46, s46, 10
	s_lshl_b32 s48, s47, 10
	s_add_i32 s36, s36, 0
	s_add_i32 s59, s59, 0
	v_add_u32_e32 v12, s58, v2
	s_and_b32 s58, s2, 15
	s_ashr_i32 s5, s4, 31
	s_ashr_i32 s39, s38, 31
	s_ashr_i32 s41, s40, 31
	s_ashr_i32 s43, s42, 31
	s_ashr_i32 s45, s44, 31
	s_ashr_i32 s47, s46, 31
	s_ashr_i32 s49, s48, 31
	s_add_i32 s36, s36, 0x1d800
	s_add_i32 s59, s59, 0x1e000
	s_lshl_b64 s[56:57], s[56:57], 23
	s_lshl_b32 s58, s58, 8
	s_lshl_b64 s[50:51], s[50:51], 1
	s_add_u32 s50, s50, s58
	s_addc_u32 s51, s51, 0
	v_and_b32_e32 v0, 48, v0
	s_add_u32 s50, s50, s56
	v_lshlrev_b32_e32 v76, 10, v0
	s_addc_u32 s51, s51, s57
	v_mul_u32_u24_e32 v16, 0x84, v1
	v_cmp_eq_u32_e64 s[0:1], 0, v1
	v_lshlrev_b32_e32 v87, 2, v85
	s_waitcnt vmcnt(0)
	v_add_u32_e32 v93, s59, v3
	v_mul_u32_u24_e32 v96, 0x88, v1
	v_lshl_add_u64 v[0:1], s[50:51], 0, v[76:77]
	s_waitcnt vmcnt(0)
	ds_write_b128 v90, v[4:7]
	ds_write_b128 v90, v[8:11] offset:16
	v_mov_b32_e32 v3, v77
	s_waitcnt lgkmcnt(0)
	s_barrier
	v_or_b32_e32 v92, 16, v87
	v_or_b32_e32 v91, 32, v87
	v_or_b32_e32 v88, 48, v87
	v_or_b32_e32 v86, 51, v87
	v_or_b32_e32 v95, 1, v87
	v_lshl_add_u64 v[0:1], v[0:1], 0, v[2:3]
	v_lshlrev_b32_e32 v4, 7, v85
	v_lshlrev_b32_e32 v5, 5, v92
	v_lshlrev_b32_e32 v6, 5, v91
	v_lshlrev_b32_e32 v7, 5, v88
	v_lshlrev_b32_e32 v8, 5, v86
	v_mul_u32_u24_e32 v9, 0x440, v85
	v_mul_u32_u24_e32 v10, 0x110, v95
	v_lshl_add_u64 v[82:83], s[22:23], 0, v[0:1]
	v_add_u32_e32 v0, 0, v17
	v_lshlrev_b32_e32 v89, 3, v85
	v_add_u32_e32 v94, s59, v18
	s_mov_b64 s[50:51], 0
	v_lshlrev_b32_e32 v76, 1, v16
	v_add_u32_e32 v97, s36, v5
	v_add_u32_e32 v98, s36, v6
	v_add_u32_e32 v99, s36, v7
	v_add_u32_e32 v100, s36, v8
	v_add_u32_e32 v101, 0x1d800, v0
	v_mov_b32_e32 v102, 0x358637bd
	s_mov_b32 s63, 0x800000
	v_add_u32_e32 v103, v12, v9
	v_add_u32_e32 v104, v12, v10
	s_mov_b32 s64, 0x85ab000
	s_mov_b32 s65, 0x85ad000
	s_mov_b32 s66, 0x85bb000
	s_mov_b32 s67, 0x85bd000
	s_mov_b32 s68, 0x85cb000
	s_mov_b32 s69, 0x85cd000
	s_mov_b32 s70, 0x85db000
	s_mov_b32 s71, 0x85dd000
	v_mov_b32_e32 v105, 0x120000
	v_add_u32_e32 v106, s36, v4
	v_mbcnt_lo_u32_b32 v217, -1, 0
	v_mbcnt_hi_u32_b32 v217, -1, v217
	v_bfe_u32 v218, v217, 2, 1
	v_lshl_add_u32 v216, v218, 10, v106
	v_bfe_u32 v218, v217, 3, 1
	v_lshl_add_u32 v216, v218, 9, v216
	v_and_b32_e32 v218, 1, v217
	v_lshl_add_u32 v216, v218, 6, v216
	v_bfe_u32 v218, v217, 1, 1
	v_lshl_add_u32 v216, v218, 5, v216
	s_mov_b32 s92, 0xaaaaaaaa
	s_mov_b32 s93, 0xaaaaaaaa
	s_mov_b32 s94, 0xcccccccc
	s_mov_b32 s95, 0xcccccccc
	v_mov_b32_e32 v28, 0
	v_mov_b32_e32 v29, v77
	v_mov_b32_e32 v30, v77
	v_mov_b32_e32 v31, v77
	v_mov_b32_e32 v24, 0
	v_mov_b32_e32 v25, v77
	v_mov_b32_e32 v26, v77
	v_mov_b32_e32 v27, v77
	v_mov_b32_e32 v20, 0
	v_mov_b32_e32 v21, v77
	v_mov_b32_e32 v22, v77
	v_mov_b32_e32 v23, v77
	v_mov_b32_e32 v16, 0
	v_mov_b32_e32 v17, v77
	v_mov_b32_e32 v18, v77
	v_mov_b32_e32 v19, v77
	v_mov_b32_e32 v12, 0
	v_mov_b32_e32 v13, v77
	v_mov_b32_e32 v14, v77
	v_mov_b32_e32 v15, v77
	v_mov_b32_e32 v8, 0
	v_mov_b32_e32 v9, v77
	v_mov_b32_e32 v10, v77
	v_mov_b32_e32 v11, v77
	v_mov_b32_e32 v4, 0
	v_mov_b32_e32 v5, v77
	v_mov_b32_e32 v6, v77
	v_mov_b32_e32 v7, v77
	v_mov_b32_e32 v0, 0
	v_mov_b32_e32 v1, v77
	v_mov_b32_e32 v2, v77
	s_branch .LBB0_918

; #define SCAN_COPY(srcbase, bufidx) do { _Pragma("unroll") for (int k = 0; k < 8; ++k) { const int pc = wave + 8 * k; if (pc < IMG_PIECES) \
;         __builtin_amdgcn_global_load_lds((const unsigned*)((srcbase) + pc * 1024 + lane * 16), (LAS unsigned*)(lds + (bufidx) * IMG_BYTES + pc * 1024), 16, 0, 0); } } while (0)
; #define SCAN_LOAD(n_, uu, z0, z1, gl) do { const float* U_ = U0 + (size_t)(n_) * 8192; const bf16_t* Z_ = Z0 + (size_t)(n_) * 64 * NQ; \
;         z0 = *(const u32x4*)Z_; z1 = *(const u32x4*)(Z_ + 8); \
;         _Pragma("unroll") for (int mm = 0; mm < 4; ++mm) uu[mm] = *(const f32x4*)(U_ + mm * 256); \
;         gl = GL[unit0 + (n_)]; } while (0)
; __device__ __forceinline__ void phase_scan(const Params& p, LAS unsigned char* lds, int bh, int wave_s) {
;     ...
;         { const int np = hasn ? n + 1 : n;
;           SCAN_COPY(chunk0 + (size_t)np * IMG_BYTES, cur ^ 1); SCAN_LOAD(np, unext, zr0, zr1, glnext); }
;         bf16_t ov[16];
;         bf16x8 Sb[4];
; #pragma unroll
;         for (int s = 0; s < 4; ++s) Sb[s] = acc2frag(Sacc[2 * s], Sacc[2 * s + 1]);
;         f32x4 vn[4], o[4];
;         bf16x8 wf[2][4], qf[2][4];
; #pragma unroll
;         for (int s = 0; s < 4; ++s) { wf[0][s] = ldfrag(img + IMG_WD + fr * SWD + 32 * s + 4 * fq); qf[0][s] = ldfrag(img + IMG_QD + fr * SWD + 32 * s + 4 * fq); }
; #pragma unroll
;         for (int mm = 0; mm < 4; ++mm) {
;             if (mm < 3) {
; #pragma unroll
;                 for (int s = 0; s < 4; ++s) { wf[(mm + 1) & 1][s] = ldfrag(img + IMG_WD + (16 * (mm + 1) + fr) * SWD + 32 * s + 4 * fq); qf[(mm + 1) & 1][s] = ldfrag(img + IMG_QD + (16 * (mm + 1) + fr) * SWD + 32 * s + 4 * fq); } }
;             f32x4 c = (f32x4){0.f, 0.f, 0.f, 0.f}, d = (f32x4){0.f, 0.f, 0.f, 0.f};
; #pragma unroll
;             for (int s = 0; s < 4; ++s) {
;                 c = __builtin_amdgcn_mfma_f32_16x16x32_bf16(wf[mm & 1][s], Sb[s], c, 0, 0, 0);
;                 d = __builtin_amdgcn_mfma_f32_16x16x32_bf16(qf[mm & 1][s], Sb[s], d, 0, 0, 0);
;             }
;             vn[mm] = ucur[mm] - c; o[mm] = d;
;         }
.LBB0_934:
	s_mul_i32 s36, s57, 0xec00
	s_mov_b32 s57, s37
	s_lshl_b64 s[60:61], s[56:57], 15
	s_ashr_i32 s57, s56, 31
	s_lshl_b64 s[58:59], s[56:57], 2
	s_add_u32 s58, s25, s58
	s_addc_u32 s59, s62, s59
	s_add_i32 s36, s36, 0
	v_lshlrev_b32_e32 v107, 1, v87
	v_add3_u32 v116, s36, v76, v107
	ds_read2_b64 v[48:51], v116 offset1:4
	v_add_u32_e32 v120, 0x4000, v116
	ds_read2_b64 v[64:67], v116 offset0:8 offset1:12
	ds_read2_b64 v[60:63], v120 offset0:64 offset1:68
	v_cvt_pk_bf16_f32 v56, v28, v29
	v_cvt_pk_bf16_f32 v57, v30, v31
	v_cvt_pk_bf16_f32 v58, v24, v25
	v_cvt_pk_bf16_f32 v59, v26, v27
	ds_read2_b64 v[68:71], v120 offset0:72 offset1:76
	v_cvt_pk_bf16_f32 v52, v20, v21
	s_waitcnt lgkmcnt(0)
	v_mfma_f32_16x16x32_bf16 v[48:51], v[48:51], v[56:59], 0
	v_cvt_pk_bf16_f32 v53, v22, v23
	v_cvt_pk_bf16_f32 v54, v16, v17
	v_cvt_pk_bf16_f32 v55, v18, v19
	ds_read2_b64 v[112:115], v116 offset0:16 offset1:20
	v_mfma_f32_16x16x32_bf16 v[60:63], v[60:63], v[56:59], 0
	ds_read2_b64 v[116:119], v116 offset0:24 offset1:28
	v_cvt_pk_bf16_f32 v108, v12, v13
	v_cvt_pk_bf16_f32 v109, v14, v15
	v_mfma_f32_16x16x32_bf16 v[48:51], v[64:67], v[52:55], v[48:51]
	ds_read2_b64 v[64:67], v120 offset0:80 offset1:84
	v_cvt_pk_bf16_f32 v110, v8, v9
	v_cvt_pk_bf16_f32 v111, v10, v11
	v_mfma_f32_16x16x32_bf16 v[60:63], v[68:71], v[52:55], v[60:63]
	v_add3_u32 v107, s36, v107, v76
	v_cvt_pk_bf16_f32 v68, v4, v5
	v_cvt_pk_bf16_f32 v69, v6, v7
	s_waitcnt lgkmcnt(0)
	v_mfma_f32_16x16x32_bf16 v[48:51], v[112:115], v[108:111], v[48:51]
	v_cvt_pk_bf16_f32 v70, v0, v1
	v_cvt_pk_bf16_f32 v71, v2, v3
	v_add_u32_e32 v124, 0x1000, v107
	v_mfma_f32_16x16x32_bf16 v[60:63], v[64:67], v[108:111], v[60:63]
	s_mov_b32 m0, s86
	s_nop 0
	global_load_lds_dwordx4 v[204:205], off
	ds_read2_b64 v[64:67], v120 offset0:88 offset1:92
	v_add_u32_e32 v125, 0x5000, v107
	ds_read2_b64 v[120:123], v125 offset0:88 offset1:92
	v_mfma_f32_16x16x32_bf16 v[112:115], v[116:119], v[68:71], v[48:51]
	ds_read2_b64 v[116:119], v124 offset0:16 offset1:20
	v_add_u32_e32 v132, 0x2000, v107
	v_add_u32_e32 v133, 0x6000, v107
	s_waitcnt lgkmcnt(0)
	v_mfma_f32_16x16x32_bf16 v[48:51], v[64:67], v[68:71], v[60:63]
	ds_read2_b64 v[128:131], v133 offset0:104 offset1:108
	s_nop 1
	ds_read2_b64 v[60:63], v125 offset0:80 offset1:84
	v_add_u32_e32 v137, 0x3000, v107
	v_mfma_f32_16x16x32_bf16 v[64:67], v[116:119], v[56:59], 0
	ds_read2_b64 v[116:119], v124 offset0:24 offset1:28
	v_sub_f32_e32 v136, v35, v115
	v_sub_f32_e32 v138, v34, v114
	s_waitcnt lgkmcnt(0)
	v_mfma_f32_16x16x32_bf16 v[60:63], v[60:63], v[56:59], 0
	v_add_u32_e32 v107, 0x7000, v107
	v_pk_mul_f32 v[30:31], v[30:31], v[84:85] op_sel_hi:[1,0]
	v_pk_mul_f32 v[28:29], v[28:29], v[84:85] op_sel_hi:[1,0]
	v_mfma_f32_16x16x32_bf16 v[64:67], v[116:119], v[52:55], v[64:67]
	ds_read2_b64 v[116:119], v124 offset0:32 offset1:36
	v_pk_mul_f32 v[26:27], v[26:27], v[84:85] op_sel_hi:[1,0]
	v_pk_mul_f32 v[24:25], v[24:25], v[84:85] op_sel_hi:[1,0]
	v_mfma_f32_16x16x32_bf16 v[60:63], v[120:123], v[52:55], v[60:63]
	s_mov_b32 m0, s87
	s_nop 0
	global_load_lds_dwordx4 v[206:207], off
	ds_read2_b64 v[120:123], v125 offset0:96 offset1:100
	v_pk_mul_f32 v[22:23], v[22:23], v[84:85] op_sel_hi:[1,0]
	v_pk_mul_f32 v[20:21], v[20:21], v[84:85] op_sel_hi:[1,0]
	s_waitcnt lgkmcnt(0)
	v_mfma_f32_16x16x32_bf16 v[64:67], v[116:119], v[108:111], v[64:67]
	ds_read2_b64 v[116:119], v124 offset0:40 offset1:44
	v_pk_mul_f32 v[18:19], v[18:19], v[84:85] op_sel_hi:[1,0]
	v_pk_mul_f32 v[16:17], v[16:17], v[84:85] op_sel_hi:[1,0]
	v_mfma_f32_16x16x32_bf16 v[60:63], v[120:123], v[108:111], v[60:63]
	ds_read2_b64 v[120:123], v125 offset0:104 offset1:108
	ds_read2_b64 v[124:127], v132 offset0:40 offset1:44
	v_pk_mul_f32 v[14:15], v[14:15], v[84:85] op_sel_hi:[1,0]
	s_waitcnt lgkmcnt(0)
	v_mfma_f32_16x16x32_bf16 v[64:67], v[116:119], v[68:71], v[64:67]
	ds_read2_b64 v[116:119], v132 offset0:32 offset1:36
	v_pk_mul_f32 v[12:13], v[12:13], v[84:85] op_sel_hi:[1,0]
	v_pk_mul_f32 v[10:11], v[10:11], v[84:85] op_sel_hi:[1,0]
	v_mfma_f32_16x16x32_bf16 v[60:63], v[120:123], v[68:71], v[60:63]
	ds_read2_b64 v[120:123], v133 offset0:96 offset1:100
	s_nop 2
	v_sub_f32_e32 v139, v37, v65
	v_sub_f32_e32 v140, v36, v64
	s_waitcnt lgkmcnt(0)
	v_mfma_f32_16x16x32_bf16 v[116:119], v[116:119], v[56:59], 0
	v_mul_f32_e64 v8, v8, v84
	v_mul_f32_e64 v9, v9, v84
	v_pk_mul_f32 v[6:7], v[6:7], v[84:85] op_sel_hi:[1,0]
	v_pk_mul_f32 v[4:5], v[4:5], v[84:85] op_sel_hi:[1,0]
	v_mfma_f32_16x16x32_bf16 v[120:123], v[120:123], v[56:59], 0
	s_mov_b32 m0, s88
	s_nop 0
	global_load_lds_dwordx4 v[208:209], off
	v_mul_f32_e64 v2, v2, v84
	v_mul_f32_e64 v3, v3, v84
	v_pk_mul_f32 v[0:1], v[0:1], v[84:85] op_sel_hi:[1,0]
	v_mfma_f32_16x16x32_bf16 v[116:119], v[124:127], v[52:55], v[116:119]
	ds_read2_b64 v[124:127], v132 offset0:48 offset1:52
	v_mfma_f32_16x16x32_bf16 v[120:123], v[128:131], v[52:55], v[120:123]
	ds_read2_b64 v[128:131], v133 offset0:112 offset1:116
	s_waitcnt lgkmcnt(0)
	v_mfma_f32_16x16x32_bf16 v[116:119], v[124:127], v[108:111], v[116:119]
	ds_read2_b64 v[124:127], v132 offset0:56 offset1:60
	ds_read2_b64 v[132:135], v133 offset0:120 offset1:124
	v_mfma_f32_16x16x32_bf16 v[120:123], v[128:131], v[108:111], v[120:123]
	ds_read2_b64 v[128:131], v137 offset0:48 offset1:52
	s_waitcnt lgkmcnt(0)
	v_mfma_f32_16x16x32_bf16 v[120:123], v[132:135], v[68:71], v[120:123]
	v_sub_f32_e32 v132, v33, v113
	v_sub_f32_e32 v133, v32, v112
	ds_read2_b64 v[32:35], v137 offset0:56 offset1:60
	v_mfma_f32_16x16x32_bf16 v[112:115], v[128:131], v[56:59], 0
	s_mov_b32 m0, s89
	s_nop 0
	global_load_lds_dwordx4 v[210:211], off
	ds_read2_b64 v[128:131], v137 offset0:64 offset1:68
	v_sub_f32_e32 v134, v39, v67
	v_sub_f32_e32 v135, v38, v66
	v_mfma_f32_16x16x32_bf16 v[116:119], v[124:127], v[68:71], v[116:119]
	ds_read2_b64 v[124:127], v107 offset0:112 offset1:116
	ds_read2_b64 v[36:39], v137 offset0:72 offset1:76
	s_waitcnt lgkmcnt(0)
; __device__ __forceinline__ void phase_scan(const Params& p, LAS unsigned char* lds, int bh, int wave_s) {
;     ...
;         for (int mm = 0; mm < 4; ++mm) {
;             if (mm < 3) {
; #pragma unroll
;                 for (int s = 0; s < 4; ++s) { wf[(mm + 1) & 1][s] = ldfrag(img + IMG_WD + (16 * (mm + 1) + fr) * SWD + 32 * s + 4 * fq); qf[(mm + 1) & 1][s] = ldfrag(img + IMG_QD + (16 * (mm + 1) + fr) * SWD + 32 * s + 4 * fq); } }
;             f32x4 c = (f32x4){0.f, 0.f, 0.f, 0.f}, d = (f32x4){0.f, 0.f, 0.f, 0.f};
; #pragma unroll
;             for (int s = 0; s < 4; ++s) {
;                 c = __builtin_amdgcn_mfma_f32_16x16x32_bf16(wf[mm & 1][s], Sb[s], c, 0, 0, 0);
;                 d = __builtin_amdgcn_mfma_f32_16x16x32_bf16(qf[mm & 1][s], Sb[s], d, 0, 0, 0);
;             }
;             vn[mm] = ucur[mm] - c; o[mm] = d;
;         }
;         bf16x8 kq[4][2], kt[4][2];
; #pragma unroll
;         for (int mm = 0; mm < 4; ++mm)
; #pragma unroll
;             for (int s = 0; s < 2; ++s) kq[mm][s] = ldfrag(img + IMG_QK + (16 * mm + fr) * SKT + 32 * s + 4 * fq);
; #pragma unroll
;         for (int m = 0; m < 4; ++m)
; #pragma unroll
;             for (int s = 0; s < 2; ++s) kt[m][s] = ldfrag(img + IMG_KT + (16 * m + fr) * SKT + 32 * s + 4 * fq);
;         bf16x8 vb[2];
; #pragma unroll
;         for (int s = 0; s < 2; ++s) vb[s] = acc2frag(vn[2 * s], vn[2 * s + 1]);
; #pragma unroll
;         for (int mm = 0; mm < 4; ++mm)
; #pragma unroll
;             for (int s = 0; s < 2; ++s) o[mm] = __builtin_amdgcn_mfma_f32_16x16x32_bf16(kq[mm][s], vb[s], o[mm], 0, 0, 0);
	v_mfma_f32_16x16x32_bf16 v[32:35], v[32:35], v[52:55], v[112:115]
	v_mfma_f32_16x16x32_bf16 v[32:35], v[128:131], v[108:111], v[32:35]
	v_add3_u32 v130, s36, v89, v96
	s_nop 1
	v_sub_f32_e32 v116, v40, v116
	v_add_u32_e32 v40, 0xc800, v130
	v_mfma_f32_16x16x32_bf16 v[56:59], v[124:127], v[56:59], 0
	ds_read2_b64 v[64:67], v107 offset0:120 offset1:124
	ds_read2_b64 v[112:115], v107 offset0:128 offset1:132
	ds_read2_b64 v[124:127], v107 offset0:136 offset1:140
	v_sub_f32_e32 v107, v43, v119
	v_sub_f32_e32 v118, v42, v118
	v_mfma_f32_16x16x32_bf16 v[32:35], v[36:39], v[68:71], v[32:35]
	v_sub_f32_e32 v117, v41, v117
	v_add_u32_e32 v131, 0x8000, v130
	s_nop 5
	v_sub_f32_e32 v119, v47, v35
	v_sub_f32_e32 v128, v46, v34
	s_waitcnt lgkmcnt(0)
	v_mfma_f32_16x16x32_bf16 v[34:37], v[64:67], v[52:55], v[56:59]
	s_mov_b32 m0, s90
	s_nop 0
	global_load_lds_dwordx4 v[212:213], off
	v_sub_f32_e32 v52, v45, v33
	v_sub_f32_e32 v53, v44, v32
	v_add_u32_e32 v54, 0xd000, v130
	v_mfma_f32_16x16x32_bf16 v[32:35], v[112:115], v[108:111], v[34:37]
	s_nop 3
	ds_read2_b64 v[36:39], v40 offset1:4
	ds_read2_b64 v[40:43], v40 offset0:8 offset1:12
	v_cvt_pk_bf16_f32 v108, v133, v132
	v_cvt_pk_bf16_f32 v109, v138, v136
	v_cvt_pk_bf16_f32 v110, v140, v139
	v_cvt_pk_bf16_f32 v111, v135, v134
	v_mfma_f32_16x16x32_bf16 v[44:47], v[124:127], v[68:71], v[32:35]
	v_cvt_pk_bf16_f32 v112, v116, v117
	v_cvt_pk_bf16_f32 v113, v118, v107
	v_cvt_pk_bf16_f32 v114, v53, v52
	ds_read2_b64 v[32:35], v54 offset0:16 offset1:20
	s_waitcnt lgkmcnt(0)
	v_mfma_f32_16x16x32_bf16 v[36:39], v[36:39], v[108:111], v[48:51]
	v_cvt_pk_bf16_f32 v115, v128, v119
	v_lshl_add_u64 v[128:129], v[80:81], 0, s[60:61]
	s_nop 0
	v_mfma_f32_16x16x32_bf16 v[68:71], v[40:43], v[112:115], v[36:39]
	v_add_u32_e32 v48, 0xd800, v130
	ds_read2_b64 v[40:43], v48 offset0:32 offset1:36
	ds_read2_b64 v[56:59], v48 offset0:40 offset1:44
	s_nop 0
	ds_read2_b64 v[36:39], v54 offset0:24 offset1:28
	v_mfma_f32_16x16x32_bf16 v[32:35], v[32:35], v[108:111], v[60:63]
	s_nop 1
	s_nop 0
	s_waitcnt lgkmcnt(0)
	v_mfma_f32_16x16x32_bf16 v[64:67], v[36:39], v[112:115], v[32:35]
	s_cmp_lt_u32 s4, 0xc00
	s_cbranch_scc0 .Lscan_dma7_skip
	s_mov_b32 m0, s91
	s_nop 0
	global_load_lds_dwordx4 v[214:215], off
; __device__ __forceinline__ void phase_scan(const Params& p, LAS unsigned char* lds, int bh, int wave_s) {
;     ...
;         for (int m = 0; m < 4; ++m) {
;             f32x4 c = Sacc[m] * glcur;
; #pragma unroll
;             for (int s = 0; s < 2; ++s) c = __builtin_amdgcn_mfma_f32_16x16x32_bf16(kt[m][s], vb[s], c, 0, 0, 0);
;             Sacc[m] = c;
;         }
; #pragma unroll
;         for (int m = 0; m < 4; ++m) {
;             f32x4 c = Sacc[m + 4] * glcur;
; #pragma unroll
;             for (int s = 0; s < 2; ++s) c = __builtin_amdgcn_mfma_f32_16x16x32_bf16(kq[m][s], vb[s], c, 0, 0, 0);
;             Sacc[m + 4] = c;
;         }
; #pragma unroll
;         for (int mm = 0; mm < 4; ++mm)
; #pragma unroll
;             for (int rg = 0; rg < 4; ++rg) { const float sr = dpp_sum16(o[mm][rg] * o[mm][rg]);
;                 if (fr == 0) SCR[(16 * mm + 4 * fq + rg) * 8 + wave] = sr; }
.Lscan_dma7_skip:
	v_add_u32_e32 v38, 0xe000, v130
	ds_read2_b64 v[116:119], v38 offset0:48 offset1:52
	v_mad_u64_u32 v[36:37], s[56:57], s56, v105, v[78:79]
	v_mfma_f32_16x16x32_bf16 v[32:35], v[40:43], v[108:111], v[120:123]
	global_load_dwordx4 v[48:51], v[36:37], off offset:16
	global_load_dwordx4 v[52:55], v[36:37], off
	s_nop 0
	ds_read2_b64 v[120:123], v38 offset0:56 offset1:60
	v_mfma_f32_16x16x32_bf16 v[60:63], v[56:59], v[112:115], v[32:35]
	s_nop 2
	global_load_dwordx4 v[32:35], v[128:129], off
	global_load_dwordx4 v[36:39], v[128:129], off offset:1024
	ds_read2_b64 v[124:127], v131 offset0:128 offset1:132
	s_nop 0
	s_waitcnt lgkmcnt(0)
	v_mfma_f32_16x16x32_bf16 v[56:59], v[116:119], v[108:111], v[44:47]
	global_load_dwordx4 v[40:43], v[128:129], off offset:2048
	s_nop 1
	global_load_dwordx4 v[44:47], v[128:129], off offset:3072
	global_load_dword v107, v77, s[58:59]
	ds_read2_b64 v[116:119], v131 offset0:136 offset1:140
	v_add_u32_e32 v128, 0x8800, v130
	v_mfma_f32_16x16x32_bf16 v[56:59], v[120:123], v[112:115], v[56:59]
	s_nop 0
	v_mfma_f32_16x16x32_bf16 v[28:31], v[124:127], v[108:111], v[28:31]
	ds_read2_b64 v[120:123], v128 offset0:144 offset1:148
	ds_read2_b64 v[124:127], v128 offset0:152 offset1:156
	v_add_u32_e32 v128, 0x9000, v130
	s_nop 0
	s_waitcnt lgkmcnt(0)
	v_mfma_f32_16x16x32_bf16 v[24:27], v[120:123], v[108:111], v[24:27]
	v_mfma_f32_16x16x32_bf16 v[28:31], v[116:119], v[112:115], v[28:31]
	ds_read2_b64 v[116:119], v128 offset0:160 offset1:164
	ds_read2_b64 v[120:123], v128 offset0:168 offset1:172
	v_mfma_f32_16x16x32_bf16 v[24:27], v[124:127], v[112:115], v[24:27]
	v_add_u32_e32 v124, 0x9800, v130
	s_waitcnt lgkmcnt(0)
	v_mfma_f32_16x16x32_bf16 v[20:23], v[116:119], v[108:111], v[20:23]
	ds_read2_b64 v[116:119], v124 offset0:176 offset1:180
	ds_read2_b64 v[124:127], v124 offset0:184 offset1:188
	v_mfma_f32_16x16x32_bf16 v[20:23], v[120:123], v[112:115], v[20:23]
	v_add_u32_e32 v120, 0xa000, v130
	s_waitcnt lgkmcnt(0)
	v_mfma_f32_16x16x32_bf16 v[16:19], v[116:119], v[108:111], v[16:19]
	ds_read2_b64 v[116:119], v120 offset0:192 offset1:196
	ds_read2_b64 v[120:123], v120 offset0:200 offset1:204
	v_mfma_f32_16x16x32_bf16 v[16:19], v[124:127], v[112:115], v[16:19]
	v_add_u32_e32 v124, 0xa800, v130
	s_waitcnt lgkmcnt(0)
	v_mfma_f32_16x16x32_bf16 v[12:15], v[116:119], v[108:111], v[12:15]
	ds_read2_b64 v[116:119], v124 offset0:208 offset1:212
	ds_read2_b64 v[124:127], v124 offset0:216 offset1:220
	v_mfma_f32_16x16x32_bf16 v[12:15], v[120:123], v[112:115], v[12:15]
	v_add_u32_e32 v120, 0xb000, v130
	s_waitcnt lgkmcnt(0)
	v_mfma_f32_16x16x32_bf16 v[8:11], v[116:119], v[108:111], v[8:11]
	ds_read2_b64 v[116:119], v120 offset0:224 offset1:228
	ds_read2_b64 v[120:123], v120 offset0:232 offset1:236
	v_mfma_f32_16x16x32_bf16 v[8:11], v[124:127], v[112:115], v[8:11]
	v_add_u32_e32 v124, 0xb800, v130
	s_waitcnt lgkmcnt(0)
	v_mfma_f32_16x16x32_bf16 v[4:7], v[116:119], v[108:111], v[4:7]
	ds_read2_b64 v[116:119], v124 offset0:240 offset1:244
	ds_read2_b64 v[124:127], v124 offset0:248 offset1:252
	s_waitcnt lgkmcnt(0)
	v_mfma_f32_16x16x32_bf16 v[0:3], v[116:119], v[108:111], v[0:3]
	s_nop 0
	v_mfma_f32_16x16x32_bf16 v[4:7], v[120:123], v[112:115], v[4:7]
	v_mfma_f32_16x16x32_bf16 v[0:3], v[124:127], v[112:115], v[0:3]
	v_mul_f32_e32 v220, v68, v68
	v_mul_f32_e32 v221, v69, v69
	v_mul_f32_e32 v222, v70, v70
	v_mul_f32_e32 v223, v71, v71
	v_mul_f32_e32 v224, v64, v64
	v_mul_f32_e32 v225, v65, v65
	v_mul_f32_e32 v226, v66, v66
	v_mul_f32_e32 v227, v67, v67
	v_mul_f32_e32 v228, v60, v60
	v_mul_f32_e32 v229, v61, v61
	v_mul_f32_e32 v230, v62, v62
	v_mul_f32_e32 v231, v63, v63
	v_mul_f32_e32 v232, v56, v56
	v_mul_f32_e32 v233, v57, v57
	v_mul_f32_e32 v234, v58, v58
	v_mul_f32_e32 v235, v59, v59
	v_add_f32_dpp v220, v220, v220 row_half_mirror row_mask:0xf bank_mask:0x5
	v_add_f32_dpp v221, v221, v221 row_half_mirror row_mask:0xf bank_mask:0x5
	v_add_f32_dpp v222, v222, v222 row_half_mirror row_mask:0xf bank_mask:0x5
	v_add_f32_dpp v223, v223, v223 row_half_mirror row_mask:0xf bank_mask:0x5
	v_add_f32_dpp v224, v224, v224 row_half_mirror row_mask:0xf bank_mask:0x5
	v_add_f32_dpp v225, v225, v225 row_half_mirror row_mask:0xf bank_mask:0x5
	v_add_f32_dpp v226, v226, v226 row_half_mirror row_mask:0xf bank_mask:0x5
	v_add_f32_dpp v227, v227, v227 row_half_mirror row_mask:0xf bank_mask:0x5
	v_add_f32_dpp v220, v228, v228 row_half_mirror row_mask:0xf bank_mask:0xa
	v_add_f32_dpp v221, v229, v229 row_half_mirror row_mask:0xf bank_mask:0xa
	v_add_f32_dpp v222, v230, v230 row_half_mirror row_mask:0xf bank_mask:0xa
	v_add_f32_dpp v223, v231, v231 row_half_mirror row_mask:0xf bank_mask:0xa
	v_add_f32_dpp v224, v232, v232 row_half_mirror row_mask:0xf bank_mask:0xa
	v_add_f32_dpp v225, v233, v233 row_half_mirror row_mask:0xf bank_mask:0xa
	v_add_f32_dpp v226, v234, v234 row_half_mirror row_mask:0xf bank_mask:0xa
	v_add_f32_dpp v227, v235, v235 row_half_mirror row_mask:0xf bank_mask:0xa
	v_add_f32_dpp v220, v220, v220 row_ror:8 row_mask:0xf bank_mask:0x3
	v_add_f32_dpp v221, v221, v221 row_ror:8 row_mask:0xf bank_mask:0x3
	v_add_f32_dpp v222, v222, v222 row_ror:8 row_mask:0xf bank_mask:0x3
	v_add_f32_dpp v223, v223, v223 row_ror:8 row_mask:0xf bank_mask:0x3
	v_add_f32_dpp v220, v224, v224 row_ror:8 row_mask:0xf bank_mask:0xc
	v_add_f32_dpp v221, v225, v225 row_ror:8 row_mask:0xf bank_mask:0xc
	v_add_f32_dpp v222, v226, v226 row_ror:8 row_mask:0xf bank_mask:0xc
	v_add_f32_dpp v223, v227, v227 row_ror:8 row_mask:0xf bank_mask:0xc
	v_cndmask_b32_e64 v236, v222, v220, s[92:93]
	v_cndmask_b32_e64 v220, v220, v222, s[92:93]
	v_cndmask_b32_e64 v237, v223, v221, s[92:93]
	v_cndmask_b32_e64 v221, v221, v223, s[92:93]
	v_add_f32_dpp v220, v236, v220 quad_perm:[1,0,3,2] row_mask:0xf bank_mask:0xf
	v_add_f32_dpp v221, v237, v221 quad_perm:[1,0,3,2] row_mask:0xf bank_mask:0xf
	v_cndmask_b32_e64 v236, v221, v220, s[94:95]
	v_cndmask_b32_e64 v220, v220, v221, s[94:95]
	s_nop 1
	v_add_f32_dpp v220, v236, v220 quad_perm:[2,3,0,1] row_mask:0xf bank_mask:0xf
	ds_write_b32 v216, v220
	s_branch .LBB0_917

; __device__ __forceinline__ float bflo(unsigned w) { return __uint_as_float(w << 16); }
; __device__ __forceinline__ float bfhi(unsigned w) { return __uint_as_float(w & 0xffff0000u); }
; __device__ __forceinline__ void rms_row_b2f(const bf16_t* xrow, const float* g, float* orow, int lane) {
;     const u32x4* xr = (const u32x4*)xrow + lane; u32x4 w[4]; float s = 0.f;
; #pragma unroll
;     for (int j = 0; j < 4; ++j) { w[j] = xr[64 * j];
;         const float a0 = bflo(w[j].x), a1 = bfhi(w[j].x), a2 = bflo(w[j].y), a3 = bfhi(w[j].y), a4 = bflo(w[j].z), a5 = bfhi(w[j].z), a6 = bflo(w[j].w), a7 = bfhi(w[j].w);
;         s += ((a0 * a0 + a1 * a1) + (a2 * a2 + a3 * a3)) + ((a4 * a4 + a5 * a5) + (a6 * a6 + a7 * a7)); }
;     const float rstd = rsqrtf(wave_sum(s) * (1.f / DM) + EPS);
;     f32x4* o = (f32x4*)orow;
; #pragma unroll
;     for (int j = 0; j < 4; ++j) { const int q = (64 * j + lane) * 2; const f32x4 g0 = ((const f32x4*)g)[q], g1 = ((const f32x4*)g)[q + 1];
;         __builtin_nontemporal_store((f32x4){bflo(w[j].x) * rstd * g0.x, bfhi(w[j].x) * rstd * g0.y, bflo(w[j].y) * rstd * g0.z, bfhi(w[j].y) * rstd * g0.w}, o + q);
;         __builtin_nontemporal_store((f32x4){bflo(w[j].z) * rstd * g1.x, bfhi(w[j].z) * rstd * g1.y, bflo(w[j].w) * rstd * g1.z, bfhi(w[j].w) * rstd * g1.w}, o + q + 1); }
; }
; __global__ void __launch_bounds__(512, 2) mega(Params p) {
;     ...
;     if (IN(10)) {
;         const int tid = opaque_tid(wave_s), lane = tid & 63, wave = tid >> 6;
;         const int gw = bx * 8 + wave, NGW = G * 8;
;         for (int m = gw; m < MR; m += NGW) {
;             float* dst = (m < MP) ? p.out + O_YP + (size_t)m * DM : p.out + O_YS + (size_t)(m - MP) * DM;
;             rms_row_b2f((const bf16_t*)(ws + WS_X1) + (size_t)m * DM, p.in[23], dst, lane);
;         }
.LBB0_1412:
	s_cmp_lt_i32 s18, 11
	s_cselect_b64 s[4:5], -1, 0
	s_and_b64 s[0:1], s[4:5], s[0:1]
	s_andn2_b64 vcc, exec, s[0:1]
	s_cbranch_vccnz .LBB0_1418
	s_mov_b64 exec, -1
	v_mbcnt_lo_u32_b32 v0, -1, 0
	v_mbcnt_hi_u32_b32 v0, -1, v0
	s_lshr_b32 s84, s24, 6
	s_lshl_b32 s85, s2, 3
	s_add_i32 s85, s85, s84
	v_readlane_b32 s86, v254, 14
	v_readlane_b32 s87, v254, 15
	v_lshlrev_b32_e32 v1, 5, v0
	v_add_u32_e32 v2, 0x1000, v1
	v_lshlrev_b32_e32 v3, 4, v0
	s_nop 2
	global_load_dwordx4 v[64:67], v1, s[86:87]
	global_load_dwordx4 v[68:71], v1, s[86:87] offset:16
	global_load_dwordx4 v[72:75], v1, s[86:87] offset:2048
	global_load_dwordx4 v[76:79], v1, s[86:87] offset:2064
	global_load_dwordx4 v[80:83], v2, s[86:87]
	global_load_dwordx4 v[84:87], v2, s[86:87] offset:16
	global_load_dwordx4 v[88:91], v2, s[86:87] offset:2048
	global_load_dwordx4 v[92:95], v2, s[86:87] offset:2064
	s_lshl_b32 s88, s85, 12
	s_add_u32 s90, s22, 0x17d2a000
	s_addc_u32 s91, s23, 0
	s_add_u32 s90, s90, s88
	s_addc_u32 s91, s91, 0
	s_lshl_b32 s88, s85, 13
	s_add_u32 s92, s20, s88
	s_addc_u32 s93, s21, 0
	v_mov_b32_e32 v4, 0x358637bd
	v_xor_b32_e32 v5, 1, v0
	v_lshlrev_b32_e32 v5, 2, v5
	v_xor_b32_e32 v6, 2, v0
	v_lshlrev_b32_e32 v6, 2, v6
	v_xor_b32_e32 v7, 4, v0
	v_lshlrev_b32_e32 v7, 2, v7
	v_xor_b32_e32 v8, 8, v0
	v_lshlrev_b32_e32 v8, 2, v8
	v_xor_b32_e32 v9, 16, v0
	v_lshlrev_b32_e32 v9, 2, v9
	v_xor_b32_e32 v10, 32, v0
	v_lshlrev_b32_e32 v10, 2, v10
	global_load_dwordx4 v[24:27], v3, s[90:91]
	global_load_dwordx4 v[28:31], v3, s[90:91] offset:1024
	global_load_dwordx4 v[32:35], v3, s[90:91] offset:2048
	global_load_dwordx4 v[36:39], v3, s[90:91] offset:3072
	s_waitcnt vmcnt(0)
.Lrms10_loop:
	s_add_i32 s94, s85, 0x800
	s_cmp_lt_u32 s94, 0x2080
	s_cbranch_scc0 .Lrms10_nopf
	s_add_u32 s90, s90, 0x800000
	s_addc_u32 s91, s91, 0
	global_load_dwordx4 v[40:43], v3, s[90:91]
	global_load_dwordx4 v[44:47], v3, s[90:91] offset:1024
	global_load_dwordx4 v[48:51], v3, s[90:91] offset:2048
	global_load_dwordx4 v[52:55], v3, s[90:91] offset:3072
; __device__ __forceinline__ float bflo(unsigned w) { return __uint_as_float(w << 16); }
; __device__ __forceinline__ float bfhi(unsigned w) { return __uint_as_float(w & 0xffff0000u); }
; __device__ __forceinline__ void rms_row_b2f(const bf16_t* xrow, const float* g, float* orow, int lane) {
;     const u32x4* xr = (const u32x4*)xrow + lane; u32x4 w[4]; float s = 0.f;
; #pragma unroll
;     for (int j = 0; j < 4; ++j) { w[j] = xr[64 * j];
;         const float a0 = bflo(w[j].x), a1 = bfhi(w[j].x), a2 = bflo(w[j].y), a3 = bfhi(w[j].y), a4 = bflo(w[j].z), a5 = bfhi(w[j].z), a6 = bflo(w[j].w), a7 = bfhi(w[j].w);
;         s += ((a0 * a0 + a1 * a1) + (a2 * a2 + a3 * a3)) + ((a4 * a4 + a5 * a5) + (a6 * a6 + a7 * a7)); }
;     const float rstd = rsqrtf(wave_sum(s) * (1.f / DM) + EPS);
;     f32x4* o = (f32x4*)orow;
; #pragma unroll
;     for (int j = 0; j < 4; ++j) { const int q = (64 * j + lane) * 2; const f32x4 g0 = ((const f32x4*)g)[q], g1 = ((const f32x4*)g)[q + 1];
;         __builtin_nontemporal_store((f32x4){bflo(w[j].x) * rstd * g0.x, bfhi(w[j].x) * rstd * g0.y, bflo(w[j].y) * rstd * g0.z, bfhi(w[j].y) * rstd * g0.w}, o + q);
;         __builtin_nontemporal_store((f32x4){bflo(w[j].z) * rstd * g1.x, bfhi(w[j].z) * rstd * g1.y, bflo(w[j].w) * rstd * g1.z, bfhi(w[j].w) * rstd * g1.w}, o + q + 1); }
; }
.Lrms10_nopf:
	v_lshlrev_b32_e32 v100, 16, v24
	v_and_b32_e32 v101, 0xffff0000, v24
	v_lshlrev_b32_e32 v102, 16, v25
	v_and_b32_e32 v103, 0xffff0000, v25
	v_lshlrev_b32_e32 v104, 16, v26
	v_and_b32_e32 v105, 0xffff0000, v26
	v_lshlrev_b32_e32 v106, 16, v27
	v_and_b32_e32 v107, 0xffff0000, v27
	v_lshlrev_b32_e32 v108, 16, v28
	v_and_b32_e32 v109, 0xffff0000, v28
	v_lshlrev_b32_e32 v110, 16, v29
	v_and_b32_e32 v111, 0xffff0000, v29
	v_lshlrev_b32_e32 v112, 16, v30
	v_and_b32_e32 v113, 0xffff0000, v30
	v_lshlrev_b32_e32 v114, 16, v31
	v_and_b32_e32 v115, 0xffff0000, v31
	v_lshlrev_b32_e32 v116, 16, v32
	v_and_b32_e32 v117, 0xffff0000, v32
	v_lshlrev_b32_e32 v118, 16, v33
	v_and_b32_e32 v119, 0xffff0000, v33
	v_lshlrev_b32_e32 v120, 16, v34
	v_and_b32_e32 v121, 0xffff0000, v34
	v_lshlrev_b32_e32 v122, 16, v35
	v_and_b32_e32 v123, 0xffff0000, v35
	v_lshlrev_b32_e32 v124, 16, v36
	v_and_b32_e32 v125, 0xffff0000, v36
	v_lshlrev_b32_e32 v126, 16, v37
	v_and_b32_e32 v127, 0xffff0000, v37
	v_lshlrev_b32_e32 v128, 16, v38
	v_and_b32_e32 v129, 0xffff0000, v38
	v_lshlrev_b32_e32 v130, 16, v39
	v_and_b32_e32 v131, 0xffff0000, v39
	v_mov_b32_e32 v16, 0
	v_mul_f32_e32 v17, v101, v101
	v_fmac_f32_e32 v17, v100, v100
	v_mul_f32_e32 v18, v103, v103
	v_fmac_f32_e32 v18, v102, v102
	v_mul_f32_e32 v19, v105, v105
	v_fmac_f32_e32 v19, v104, v104
	v_mul_f32_e32 v20, v107, v107
	v_fmac_f32_e32 v20, v106, v106
	v_add_f32_e32 v17, v17, v18
	v_add_f32_e32 v19, v19, v20
	v_add_f32_e32 v17, v17, v19
	v_add_f32_e32 v16, v16, v17
	v_mul_f32_e32 v17, v109, v109
	v_fmac_f32_e32 v17, v108, v108
	v_mul_f32_e32 v18, v111, v111
	v_fmac_f32_e32 v18, v110, v110
	v_mul_f32_e32 v19, v113, v113
	v_fmac_f32_e32 v19, v112, v112
	v_mul_f32_e32 v20, v115, v115
	v_fmac_f32_e32 v20, v114, v114
	v_add_f32_e32 v17, v17, v18
	v_add_f32_e32 v19, v19, v20
	v_add_f32_e32 v17, v17, v19
	v_add_f32_e32 v16, v16, v17
	v_mul_f32_e32 v17, v117, v117
	v_fmac_f32_e32 v17, v116, v116
	v_mul_f32_e32 v18, v119, v119
	v_fmac_f32_e32 v18, v118, v118
	v_mul_f32_e32 v19, v121, v121
	v_fmac_f32_e32 v19, v120, v120
	v_mul_f32_e32 v20, v123, v123
	v_fmac_f32_e32 v20, v122, v122
	v_add_f32_e32 v17, v17, v18
	v_add_f32_e32 v19, v19, v20
	v_add_f32_e32 v17, v17, v19
	v_add_f32_e32 v16, v16, v17
	v_mul_f32_e32 v17, v125, v125
	v_fmac_f32_e32 v17, v124, v124
	v_mul_f32_e32 v18, v127, v127
	v_fmac_f32_e32 v18, v126, v126
	v_mul_f32_e32 v19, v129, v129
	v_fmac_f32_e32 v19, v128, v128
	v_mul_f32_e32 v20, v131, v131
	v_fmac_f32_e32 v20, v130, v130
	v_add_f32_e32 v17, v17, v18
	v_add_f32_e32 v19, v19, v20
	v_add_f32_e32 v17, v17, v19
	v_add_f32_e32 v16, v16, v17
	ds_bpermute_b32 v17, v5, v16
	s_waitcnt lgkmcnt(0)
	v_add_f32_e32 v16, v16, v17
	ds_bpermute_b32 v17, v6, v16
	s_waitcnt lgkmcnt(0)
	v_add_f32_e32 v16, v16, v17
	ds_bpermute_b32 v17, v7, v16
	s_waitcnt lgkmcnt(0)
	v_add_f32_e32 v16, v16, v17
	ds_bpermute_b32 v17, v8, v16
	s_waitcnt lgkmcnt(0)
	v_add_f32_e32 v16, v16, v17
	ds_bpermute_b32 v17, v9, v16
	s_waitcnt lgkmcnt(0)
	v_add_f32_e32 v16, v16, v17
	ds_bpermute_b32 v17, v10, v16
	s_waitcnt lgkmcnt(0)
	v_add_f32_e32 v16, v16, v17
	v_fmamk_f32 v16, v16, 0x3a000000, v4
	v_rsq_f32_e32 v16, v16
	s_nop 0
	v_mul_f32_e32 v100, v100, v16
	v_mul_f32_e32 v101, v101, v16
	v_mul_f32_e32 v102, v102, v16
	v_mul_f32_e32 v103, v103, v16
	v_mul_f32_e32 v104, v104, v16
	v_mul_f32_e32 v105, v105, v16
	v_mul_f32_e32 v106, v106, v16
	v_mul_f32_e32 v107, v107, v16
	v_mul_f32_e32 v100, v100, v64
	v_mul_f32_e32 v101, v101, v65
	v_mul_f32_e32 v102, v102, v66
	v_mul_f32_e32 v103, v103, v67
	v_mul_f32_e32 v104, v104, v68
	v_mul_f32_e32 v105, v105, v69
	v_mul_f32_e32 v106, v106, v70
	v_mul_f32_e32 v107, v107, v71
	global_store_dwordx4 v1, v[100:103], s[92:93] nt
	global_store_dwordx4 v1, v[104:107], s[92:93] offset:16 nt
	v_mul_f32_e32 v108, v108, v16
	v_mul_f32_e32 v109, v109, v16
	v_mul_f32_e32 v110, v110, v16
	v_mul_f32_e32 v111, v111, v16
	v_mul_f32_e32 v112, v112, v16
	v_mul_f32_e32 v113, v113, v16
	v_mul_f32_e32 v114, v114, v16
	v_mul_f32_e32 v115, v115, v16
	v_mul_f32_e32 v108, v108, v72
	v_mul_f32_e32 v109, v109, v73
	v_mul_f32_e32 v110, v110, v74
	v_mul_f32_e32 v111, v111, v75
	v_mul_f32_e32 v112, v112, v76
	v_mul_f32_e32 v113, v113, v77
	v_mul_f32_e32 v114, v114, v78
	v_mul_f32_e32 v115, v115, v79
	global_store_dwordx4 v1, v[108:111], s[92:93] offset:2048 nt
	global_store_dwordx4 v1, v[112:115], s[92:93] offset:2064 nt
	v_mul_f32_e32 v116, v116, v16
	v_mul_f32_e32 v117, v117, v16
	v_mul_f32_e32 v118, v118, v16
	v_mul_f32_e32 v119, v119, v16
	v_mul_f32_e32 v120, v120, v16
	v_mul_f32_e32 v121, v121, v16
	v_mul_f32_e32 v122, v122, v16
	v_mul_f32_e32 v123, v123, v16
	v_mul_f32_e32 v116, v116, v80
	v_mul_f32_e32 v117, v117, v81
	v_mul_f32_e32 v118, v118, v82
	v_mul_f32_e32 v119, v119, v83
	v_mul_f32_e32 v120, v120, v84
	v_mul_f32_e32 v121, v121, v85
	v_mul_f32_e32 v122, v122, v86
	v_mul_f32_e32 v123, v123, v87
	global_store_dwordx4 v2, v[116:119], s[92:93] nt
	global_store_dwordx4 v2, v[120:123], s[92:93] offset:16 nt
	v_mul_f32_e32 v124, v124, v16
	v_mul_f32_e32 v125, v125, v16
	v_mul_f32_e32 v126, v126, v16
	v_mul_f32_e32 v127, v127, v16
	v_mul_f32_e32 v128, v128, v16
	v_mul_f32_e32 v129, v129, v16
	v_mul_f32_e32 v130, v130, v16
	v_mul_f32_e32 v131, v131, v16
	v_mul_f32_e32 v124, v124, v88
	v_mul_f32_e32 v125, v125, v89
	v_mul_f32_e32 v126, v126, v90
	v_mul_f32_e32 v127, v127, v91
	v_mul_f32_e32 v128, v128, v92
	v_mul_f32_e32 v129, v129, v93
	v_mul_f32_e32 v130, v130, v94
	v_mul_f32_e32 v131, v131, v95
	global_store_dwordx4 v2, v[124:127], s[92:93] offset:2048 nt
	global_store_dwordx4 v2, v[128:131], s[92:93] offset:2064 nt
	s_cmp_lt_u32 s94, 0x2080
	s_cbranch_scc0 .Lrms10_done
	s_waitcnt vmcnt(8)
	v_mov_b64_e32 v[24:25], v[40:41]
	v_mov_b64_e32 v[26:27], v[42:43]
	v_mov_b64_e32 v[28:29], v[44:45]
	v_mov_b64_e32 v[30:31], v[46:47]
	v_mov_b64_e32 v[32:33], v[48:49]
	v_mov_b64_e32 v[34:35], v[50:51]
	v_mov_b64_e32 v[36:37], v[52:53]
	v_mov_b64_e32 v[38:39], v[54:55]
	s_mov_b32 s85, s94
	s_add_u32 s92, s92, 0x1000000
	s_addc_u32 s93, s93, 0
	s_branch .Lrms10_loop
.Lrms10_done:
.LBB0_1418:
	s_endpgm
